# cmp2 phase: weight copy to LDS de-serialised (8 dwordx4 loads in flight per thread, then 8 ds_write_b128) on top of the f32-MFMA fixup
# baseline (speedup 1.0000x reference)
.LBB0_1107:
	s_or_b64 exec, exec, s[2:3]
	s_waitcnt lgkmcnt(0)
	s_barrier
	s_getreg_b32 s0, hwreg(HW_REG_HW_ID, 0, 6)
	s_and_b32 s0, s0, 63
	s_lshl_b32 s0, s0, 2
	s_add_i32 s0, s0, 0
	s_add_i32 s0, s0, 0x22ef0
	v_mov_b32_e32 v0, s0
	ds_read_b32 v0, v0
	v_mov_b32_e32 v1, v177
	s_mov_b64 s[10:11], 0x10800000
	s_mov_b64 s[8:9], 0x40000
	s_waitcnt lgkmcnt(0)
	v_readfirstlane_b32 s0, v0
	v_mbcnt_lo_u32_b32 v0, -1, v1
	v_mbcnt_hi_u32_b32 v0, -1, v0
	v_lshl_add_u32 v2, s0, 6, v0
	s_mov_b32 s0, 12
	s_mov_b32 s2, 13
	s_ashr_i32 s3, s2, 31
	s_lshl_b64 s[2:3], s[2:3], 3
	v_readlane_b32 s4, v253, 1
	v_readlane_b32 s5, v253, 2
	s_add_u32 s2, s4, s2
	s_addc_u32 s3, s5, s3
	s_load_dwordx2 s[12:13], s[2:3], 0x0
	s_movk_i32 s1, 0x4000
	s_mov_b64 s[2:3], 0xe200000
	s_mov_b64 s[4:5], 0xe300000
	v_cmp_gt_i32_e32 vcc, s1, v2
	s_and_saveexec_b64 s[6:7], vcc
	s_cbranch_execz .LBB0_1120
	v_readlane_b32 s14, v253, 1
	v_readlane_b32 s15, v253, 2
	v_readlane_b32 s0, v254, 61
	v_readlane_b32 s1, v254, 62
	v_lshlrev_b32_e32 v3, 4, v2
	s_and_b64 s[0:1], s[0:1], exec
	s_cselect_b32 s24, 0x10000, 0
	s_add_u32 s0, s14, 0x60
	s_addc_u32 s1, s15, 0
	s_load_dwordx2 s[14:15], s[0:1], 0x0
	s_waitcnt lgkmcnt(0)
	s_add_u32 s0, s14, s24
	s_addc_u32 s1, s15, 0
	global_load_dwordx4 v[20:23], v3, s[0:1]
	s_add_u32 s0, s0, 0x2000
	s_addc_u32 s1, s1, 0
	global_load_dwordx4 v[24:27], v3, s[0:1]
	s_add_u32 s0, s0, 0x2000
	s_addc_u32 s1, s1, 0
	global_load_dwordx4 v[28:31], v3, s[0:1]
	s_add_u32 s0, s0, 0x2000
	s_addc_u32 s1, s1, 0
	global_load_dwordx4 v[32:35], v3, s[0:1]
	s_add_u32 s0, s0, 0x2000
	s_addc_u32 s1, s1, 0
	global_load_dwordx4 v[36:39], v3, s[0:1]
	s_add_u32 s0, s0, 0x2000
	s_addc_u32 s1, s1, 0
	global_load_dwordx4 v[40:43], v3, s[0:1]
	s_add_u32 s0, s0, 0x2000
	s_addc_u32 s1, s1, 0
	global_load_dwordx4 v[44:47], v3, s[0:1]
	s_add_u32 s0, s0, 0x2000
	s_addc_u32 s1, s1, 0
	global_load_dwordx4 v[48:51], v3, s[0:1]
	s_waitcnt vmcnt(7)
	ds_write_b128 v3, v[20:23]
	s_waitcnt vmcnt(6)
	ds_write_b128 v3, v[24:27] offset:8192
	s_waitcnt vmcnt(5)
	ds_write_b128 v3, v[28:31] offset:16384
	s_waitcnt vmcnt(4)
	ds_write_b128 v3, v[32:35] offset:24576
	s_waitcnt vmcnt(3)
	ds_write_b128 v3, v[36:39] offset:32768
	s_waitcnt vmcnt(2)
	ds_write_b128 v3, v[40:43] offset:40960
	s_waitcnt vmcnt(1)
	ds_write_b128 v3, v[44:47] offset:49152
	s_waitcnt vmcnt(0)
	ds_write_b128 v3, v[48:51] offset:57344
	s_movk_i32 s18, 0x1ff
	s_mov_b64 s[16:17], 0x800
